# grid-barrier poll back-off: s_sleep 1 -> s_sleep 32 in the spin loops (fewer sc1 polls while waiting)
# speedup vs baseline: 1.0073x; 1.0073x over previous
.LBB0_219:
	s_sleep 32
	global_load_dword v3, v1, s[2:3] offset:32 sc1
	s_waitcnt vmcnt(0)
	v_and_b32_e32 v3, 0xffff0000, v3
	v_cmp_ne_u32_e32 vcc, v3, v2
	s_or_b64 s[4:5], vcc, s[4:5]
	s_andn2_b64 exec, exec, s[4:5]
	s_cbranch_execnz .LBB0_219

.LBB0_226:
	global_load_dword v16, v17, s[6:7] sc1
	s_waitcnt lgkmcnt(0)
	global_load_dword v1, v17, s[8:9] sc1
	global_load_dword v2, v17, s[10:11] sc1
	global_load_dword v3, v17, s[12:13] sc1
	global_load_dword v4, v17, s[14:15] sc1
	global_load_dword v5, v17, s[16:17] sc1
	global_load_dword v6, v17, s[18:19] sc1
	global_load_dword v7, v17, s[20:21] sc1
	global_load_dword v8, v17, s[22:23] sc1
	global_load_dword v9, v17, s[28:29] sc1
	global_load_dword v10, v17, s[30:31] sc1
	global_load_dword v11, v17, s[34:35] sc1
	global_load_dword v12, v17, s[36:37] sc1
	global_load_dword v13, v17, s[38:39] sc1
	global_load_dword v14, v17, s[40:41] sc1
	global_load_dword v15, v17, s[42:43] sc1
	s_mov_b64 s[44:45], -1
	s_mov_b64 s[46:47], -1
	s_waitcnt vmcnt(14)
	v_add_u32_e32 v18, v1, v16
	s_waitcnt vmcnt(13)
	v_add_u32_e32 v18, v18, v2
	s_waitcnt vmcnt(12)
	v_add_u32_e32 v18, v18, v3
	s_waitcnt vmcnt(11)
	v_add_u32_e32 v18, v18, v4
	s_waitcnt vmcnt(10)
	v_add_u32_e32 v18, v18, v5
	s_waitcnt vmcnt(9)
	v_add_u32_e32 v18, v18, v6
	s_waitcnt vmcnt(8)
	v_add_u32_e32 v18, v18, v7
	s_waitcnt vmcnt(7)
	v_add_u32_e32 v18, v18, v8
	s_waitcnt vmcnt(6)
	v_add_u32_e32 v18, v18, v9
	s_waitcnt vmcnt(5)
	v_add_u32_e32 v18, v18, v10
	s_waitcnt vmcnt(4)
	v_add_u32_e32 v18, v18, v11
	s_waitcnt vmcnt(3)
	v_add_u32_e32 v18, v18, v12
	s_waitcnt vmcnt(2)
	v_add_u32_e32 v18, v18, v13
	s_waitcnt vmcnt(1)
	v_add_u32_e32 v18, v18, v14
	s_waitcnt vmcnt(0)
	v_add_u32_e32 v18, v18, v15
	v_cmp_eq_u32_e32 vcc, s50, v18
	s_cbranch_vccnz .LBB0_225
	s_and_b32 s44, s51, 0xff
	s_cmp_eq_u32 s44, 0
	s_mov_b64 s[44:45], -1
	s_mov_b64 s[48:49], -1
	s_sleep 32
	s_cbranch_scc1 .LBB0_230
	s_and_b64 vcc, exec, s[48:49]
	s_cbranch_vccz .LBB0_225

.LBB0_244:
	s_and_b32 s18, s22, 0xff
	s_mov_b64 s[16:17], -1
	s_cmp_lg_u32 s18, 0
	s_mov_b64 s[20:21], -1
	s_sleep 32
	s_cbranch_scc0 .LBB0_247
	s_and_b64 vcc, exec, s[20:21]
	s_cbranch_vccz .LBB0_243

.LBB0_261:
	s_and_b32 s18, s28, 0xff
	s_cmp_lg_u32 s18, 0
	s_mov_b64 s[20:21], -1
	s_sleep 32
	s_cbranch_scc0 .LBB0_264
	s_mov_b64 s[22:23], -1
	s_and_b64 vcc, exec, s[20:21]
	s_cbranch_vccz .LBB0_260

.LBB0_314:
	s_sleep 32
	global_load_dword v1, v189, s[2:3] offset:32 sc1
	s_waitcnt vmcnt(0)
	v_and_b32_e32 v1, 0xffff0000, v1
	v_cmp_ne_u32_e32 vcc, v1, v0
	s_or_b64 s[20:21], vcc, s[20:21]
	s_andn2_b64 exec, exec, s[20:21]
	s_cbranch_execnz .LBB0_314

.LBB0_321:
	v_readlane_b32 s2, v254, 13
	v_readlane_b32 s3, v254, 14
	global_load_dword v3, v189, s[96:97] sc1
	s_waitcnt lgkmcnt(0)
	global_load_dword v0, v189, s[44:45] sc1
	global_load_dword v1, v189, s[82:83] sc1
	global_load_dword v2, v189, s[92:93] sc1
	s_mov_b64 s[20:21], -1
	global_load_dword v4, v189, s[2:3] sc1
	v_readlane_b32 s2, v254, 15
	v_readlane_b32 s3, v254, 16
	s_waitcnt vmcnt(3)
	v_add_u32_e32 v16, v0, v3
	s_nop 2
	global_load_dword v5, v189, s[2:3] sc1
	v_readlane_b32 s2, v254, 17
	v_readlane_b32 s3, v254, 18
	s_waitcnt vmcnt(3)
	v_add_u32_e32 v16, v16, v1
	s_waitcnt vmcnt(2)
	v_add_u32_e32 v16, v16, v2
	s_waitcnt vmcnt(1)
	v_add_u32_e32 v16, v16, v4
	s_waitcnt vmcnt(0)
	v_add_u32_e32 v16, v16, v5
	global_load_dword v6, v189, s[2:3] sc1
	v_readlane_b32 s2, v254, 19
	v_readlane_b32 s3, v254, 20
	s_waitcnt vmcnt(0)
	v_add_u32_e32 v16, v16, v6
	s_nop 2
	global_load_dword v7, v189, s[2:3] sc1
	v_readlane_b32 s2, v254, 21
	v_readlane_b32 s3, v254, 22
	s_waitcnt vmcnt(0)
	v_add_u32_e32 v16, v16, v7
	s_nop 2
	global_load_dword v8, v189, s[2:3] sc1
	v_readlane_b32 s2, v254, 23
	v_readlane_b32 s3, v254, 24
	s_waitcnt vmcnt(0)
	v_add_u32_e32 v16, v16, v8
	s_nop 2
	global_load_dword v9, v189, s[2:3] sc1
	v_readlane_b32 s2, v254, 25
	v_readlane_b32 s3, v254, 26
	s_waitcnt vmcnt(0)
	v_add_u32_e32 v16, v16, v9
	s_nop 2
	global_load_dword v10, v189, s[2:3] sc1
	v_readlane_b32 s2, v254, 27
	v_readlane_b32 s3, v254, 28
	s_nop 4
	global_load_dword v11, v189, s[2:3] sc1
	global_load_dword v12, v189, s[10:11] sc1
	global_load_dword v13, v189, s[12:13] sc1
	global_load_dword v14, v189, s[14:15] sc1
	global_load_dword v15, v189, s[16:17] sc1
	s_mov_b64 s[2:3], -1
	s_waitcnt vmcnt(5)
	v_add_u32_e32 v16, v16, v10
	s_waitcnt vmcnt(4)
	v_add_u32_e32 v16, v16, v11
	s_waitcnt vmcnt(3)
	v_add_u32_e32 v16, v16, v12
	s_waitcnt vmcnt(2)
	v_add_u32_e32 v16, v16, v13
	s_waitcnt vmcnt(1)
	v_add_u32_e32 v16, v16, v14
	s_waitcnt vmcnt(0)
	v_add_u32_e32 v16, v16, v15
	v_cmp_eq_u32_e32 vcc, s8, v16
	s_cbranch_vccnz .LBB0_320
	s_and_b32 s2, s5, 0xff
	s_cmp_eq_u32 s2, 0
	s_mov_b64 s[2:3], -1
	s_mov_b64 s[22:23], -1
	s_sleep 32
	s_cbranch_scc1 .LBB0_325
	s_and_b64 vcc, exec, s[22:23]
	s_cbranch_vccz .LBB0_320

.LBB0_339:
	s_and_b32 s6, s5, 0xff
	s_mov_b64 s[40:41], -1
	s_cmp_lg_u32 s6, 0
	s_mov_b64 s[44:45], -1
	s_sleep 32
	s_cbranch_scc0 .LBB0_342
	s_and_b64 vcc, exec, s[44:45]
	s_cbranch_vccz .LBB0_338

.LBB0_868:
	v_readlane_b32 s2, v254, 13
	v_readlane_b32 s3, v254, 14
	global_load_dword v3, v189, s[96:97] sc1
	s_waitcnt lgkmcnt(0)
	global_load_dword v0, v189, s[44:45] sc1
	global_load_dword v1, v189, s[82:83] sc1
	global_load_dword v2, v189, s[92:93] sc1
	s_mov_b64 s[20:21], -1
	global_load_dword v4, v189, s[2:3] sc1
	v_readlane_b32 s2, v254, 15
	v_readlane_b32 s3, v254, 16
	s_waitcnt vmcnt(3)
	v_add_u32_e32 v16, v0, v3
	s_nop 2
	global_load_dword v5, v189, s[2:3] sc1
	v_readlane_b32 s2, v254, 17
	v_readlane_b32 s3, v254, 18
	s_waitcnt vmcnt(3)
	v_add_u32_e32 v16, v16, v1
	s_waitcnt vmcnt(2)
	v_add_u32_e32 v16, v16, v2
	s_waitcnt vmcnt(1)
	v_add_u32_e32 v16, v16, v4
	s_waitcnt vmcnt(0)
	v_add_u32_e32 v16, v16, v5
	global_load_dword v6, v189, s[2:3] sc1
	v_readlane_b32 s2, v254, 19
	v_readlane_b32 s3, v254, 20
	s_waitcnt vmcnt(0)
	v_add_u32_e32 v16, v16, v6
	s_nop 2
	global_load_dword v7, v189, s[2:3] sc1
	v_readlane_b32 s2, v254, 21
	v_readlane_b32 s3, v254, 22
	s_waitcnt vmcnt(0)
	v_add_u32_e32 v16, v16, v7
	s_nop 2
	global_load_dword v8, v189, s[2:3] sc1
	v_readlane_b32 s2, v254, 23
	v_readlane_b32 s3, v254, 24
	s_waitcnt vmcnt(0)
	v_add_u32_e32 v16, v16, v8
	s_nop 2
	global_load_dword v9, v189, s[2:3] sc1
	v_readlane_b32 s2, v254, 25
	v_readlane_b32 s3, v254, 26
	s_waitcnt vmcnt(0)
	v_add_u32_e32 v16, v16, v9
	s_nop 2
	global_load_dword v10, v189, s[2:3] sc1
	v_readlane_b32 s2, v254, 27
	v_readlane_b32 s3, v254, 28
	s_nop 4
	global_load_dword v11, v189, s[2:3] sc1
	global_load_dword v12, v189, s[10:11] sc1
	global_load_dword v13, v189, s[12:13] sc1
	global_load_dword v14, v189, s[14:15] sc1
	global_load_dword v15, v189, s[16:17] sc1
	s_mov_b64 s[2:3], -1
	s_waitcnt vmcnt(5)
	v_add_u32_e32 v16, v16, v10
	s_waitcnt vmcnt(4)
	v_add_u32_e32 v16, v16, v11
	s_waitcnt vmcnt(3)
	v_add_u32_e32 v16, v16, v12
	s_waitcnt vmcnt(2)
	v_add_u32_e32 v16, v16, v13
	s_waitcnt vmcnt(1)
	v_add_u32_e32 v16, v16, v14
	s_waitcnt vmcnt(0)
	v_add_u32_e32 v16, v16, v15
	v_cmp_eq_u32_e32 vcc, s8, v16
	s_cbranch_vccnz .LBB0_867
	s_and_b32 s2, s4, 0xff
	s_cmp_eq_u32 s2, 0
	s_mov_b64 s[2:3], -1
	s_mov_b64 s[38:39], -1
	s_sleep 32
	s_cbranch_scc1 .LBB0_872
	s_and_b64 vcc, exec, s[38:39]
	s_cbranch_vccz .LBB0_867

.LBB0_886:
	s_and_b32 s5, s4, 0xff
	s_mov_b64 s[42:43], -1
	s_cmp_lg_u32 s5, 0
	s_mov_b64 s[46:47], -1
	s_sleep 32
	s_cbranch_scc0 .LBB0_889
	s_and_b64 vcc, exec, s[46:47]
	s_cbranch_vccz .LBB0_885

.LBB0_1047:
	s_sleep 32
	global_load_dword v1, v189, s[20:21] offset:32 sc1
	s_waitcnt vmcnt(0)
	v_and_b32_e32 v1, 0xffff0000, v1
	v_cmp_ne_u32_e32 vcc, v1, v0
	s_or_b64 s[22:23], vcc, s[22:23]
	s_andn2_b64 exec, exec, s[22:23]
	s_cbranch_execnz .LBB0_1047

.LBB0_1054:
	v_readlane_b32 s6, v254, 13
	v_readlane_b32 s7, v254, 14
	global_load_dword v3, v189, s[96:97] sc1
	s_waitcnt lgkmcnt(0)
	global_load_dword v0, v189, s[44:45] sc1
	global_load_dword v1, v189, s[82:83] sc1
	global_load_dword v2, v189, s[92:93] sc1
	s_mov_b64 s[20:21], -1
	global_load_dword v4, v189, s[6:7] sc1
	v_readlane_b32 s6, v254, 15
	v_readlane_b32 s7, v254, 16
	s_mov_b64 s[22:23], -1
	s_waitcnt vmcnt(3)
	v_add_u32_e32 v16, v0, v3
	s_nop 1
	global_load_dword v5, v189, s[6:7] sc1
	v_readlane_b32 s6, v254, 17
	v_readlane_b32 s7, v254, 18
	s_waitcnt vmcnt(3)
	v_add_u32_e32 v16, v16, v1
	s_waitcnt vmcnt(2)
	v_add_u32_e32 v16, v16, v2
	s_waitcnt vmcnt(1)
	v_add_u32_e32 v16, v16, v4
	s_waitcnt vmcnt(0)
	v_add_u32_e32 v16, v16, v5
	global_load_dword v6, v189, s[6:7] sc1
	v_readlane_b32 s6, v254, 19
	v_readlane_b32 s7, v254, 20
	s_waitcnt vmcnt(0)
	v_add_u32_e32 v16, v16, v6
	s_nop 2
	global_load_dword v7, v189, s[6:7] sc1
	v_readlane_b32 s6, v254, 21
	v_readlane_b32 s7, v254, 22
	s_waitcnt vmcnt(0)
	v_add_u32_e32 v16, v16, v7
	s_nop 2
	global_load_dword v8, v189, s[6:7] sc1
	v_readlane_b32 s6, v254, 23
	v_readlane_b32 s7, v254, 24
	s_waitcnt vmcnt(0)
	v_add_u32_e32 v16, v16, v8
	s_nop 2
	global_load_dword v9, v189, s[6:7] sc1
	v_readlane_b32 s6, v254, 25
	v_readlane_b32 s7, v254, 26
	s_waitcnt vmcnt(0)
	v_add_u32_e32 v16, v16, v9
	s_nop 2
	global_load_dword v10, v189, s[6:7] sc1
	v_readlane_b32 s6, v254, 27
	v_readlane_b32 s7, v254, 28
	s_nop 4
	global_load_dword v11, v189, s[6:7] sc1
	global_load_dword v12, v189, s[10:11] sc1
	global_load_dword v13, v189, s[12:13] sc1
	global_load_dword v14, v189, s[14:15] sc1
	global_load_dword v15, v189, s[16:17] sc1
	s_waitcnt vmcnt(5)
	v_add_u32_e32 v16, v16, v10
	s_waitcnt vmcnt(4)
	v_add_u32_e32 v16, v16, v11
	s_waitcnt vmcnt(3)
	v_add_u32_e32 v16, v16, v12
	s_waitcnt vmcnt(2)
	v_add_u32_e32 v16, v16, v13
	s_waitcnt vmcnt(1)
	v_add_u32_e32 v16, v16, v14
	s_waitcnt vmcnt(0)
	v_add_u32_e32 v16, v16, v15
	v_cmp_eq_u32_e32 vcc, s8, v16
	s_cbranch_vccnz .LBB0_1053
	s_and_b32 s6, s5, 0xff
	s_cmp_eq_u32 s6, 0
	s_mov_b64 s[38:39], -1
	s_sleep 32
	s_cbranch_scc1 .LBB0_1058
	s_and_b64 vcc, exec, s[38:39]
	s_cbranch_vccz .LBB0_1053

.LBB0_1072:
	s_and_b32 s6, s5, 0xff
	s_mov_b64 s[42:43], -1
	s_cmp_lg_u32 s6, 0
	s_mov_b64 s[46:47], -1
	s_sleep 32
	s_cbranch_scc0 .LBB0_1075
	s_and_b64 vcc, exec, s[46:47]
	s_cbranch_vccz .LBB0_1071

.LBB0_1149:
	v_readlane_b32 s2, v254, 13
	v_readlane_b32 s3, v254, 14
	global_load_dword v3, v189, s[96:97] sc1
	s_waitcnt lgkmcnt(0)
	global_load_dword v0, v189, s[44:45] sc1
	global_load_dword v1, v189, s[82:83] sc1
	global_load_dword v2, v189, s[92:93] sc1
	s_mov_b64 s[20:21], -1
	global_load_dword v4, v189, s[2:3] sc1
	v_readlane_b32 s2, v254, 15
	v_readlane_b32 s3, v254, 16
	s_waitcnt vmcnt(3)
	v_add_u32_e32 v16, v0, v3
	s_nop 2
	global_load_dword v5, v189, s[2:3] sc1
	v_readlane_b32 s2, v254, 17
	v_readlane_b32 s3, v254, 18
	s_waitcnt vmcnt(3)
	v_add_u32_e32 v16, v16, v1
	s_waitcnt vmcnt(2)
	v_add_u32_e32 v16, v16, v2
	s_waitcnt vmcnt(1)
	v_add_u32_e32 v16, v16, v4
	s_waitcnt vmcnt(0)
	v_add_u32_e32 v16, v16, v5
	global_load_dword v6, v189, s[2:3] sc1
	v_readlane_b32 s2, v254, 19
	v_readlane_b32 s3, v254, 20
	s_waitcnt vmcnt(0)
	v_add_u32_e32 v16, v16, v6
	s_nop 2
	global_load_dword v7, v189, s[2:3] sc1
	v_readlane_b32 s2, v254, 21
	v_readlane_b32 s3, v254, 22
	s_waitcnt vmcnt(0)
	v_add_u32_e32 v16, v16, v7
	s_nop 2
	global_load_dword v8, v189, s[2:3] sc1
	v_readlane_b32 s2, v254, 23
	v_readlane_b32 s3, v254, 24
	s_waitcnt vmcnt(0)
	v_add_u32_e32 v16, v16, v8
	s_nop 2
	global_load_dword v9, v189, s[2:3] sc1
	v_readlane_b32 s2, v254, 25
	v_readlane_b32 s3, v254, 26
	s_waitcnt vmcnt(0)
	v_add_u32_e32 v16, v16, v9
	s_nop 2
	global_load_dword v10, v189, s[2:3] sc1
	v_readlane_b32 s2, v254, 27
	v_readlane_b32 s3, v254, 28
	s_nop 4
	global_load_dword v11, v189, s[2:3] sc1
	global_load_dword v12, v189, s[10:11] sc1
	global_load_dword v13, v189, s[12:13] sc1
	global_load_dword v14, v189, s[14:15] sc1
	global_load_dword v15, v189, s[16:17] sc1
	s_mov_b64 s[2:3], -1
	s_waitcnt vmcnt(5)
	v_add_u32_e32 v16, v16, v10
	s_waitcnt vmcnt(4)
	v_add_u32_e32 v16, v16, v11
	s_waitcnt vmcnt(3)
	v_add_u32_e32 v16, v16, v12
	s_waitcnt vmcnt(2)
	v_add_u32_e32 v16, v16, v13
	s_waitcnt vmcnt(1)
	v_add_u32_e32 v16, v16, v14
	s_waitcnt vmcnt(0)
	v_add_u32_e32 v16, v16, v15
	v_cmp_eq_u32_e32 vcc, s8, v16
	s_cbranch_vccnz .LBB0_1148
	s_and_b32 s2, s4, 0xff
	s_cmp_eq_u32 s2, 0
	s_mov_b64 s[2:3], -1
	s_mov_b64 s[22:23], -1
	s_sleep 32
	s_cbranch_scc1 .LBB0_1153
	s_and_b64 vcc, exec, s[22:23]
	s_cbranch_vccz .LBB0_1148

.LBB0_1167:
	s_and_b32 s5, s4, 0xff
	s_mov_b64 s[40:41], -1
	s_cmp_lg_u32 s5, 0
	s_mov_b64 s[44:45], -1
	s_sleep 32
	s_cbranch_scc0 .LBB0_1170
	s_and_b64 vcc, exec, s[44:45]
	s_cbranch_vccz .LBB0_1166
